# v99: v96 + seam leaders poll the TOP arrival counter (>= target) instead of a separate generation word; last leader skips the generation bump
# speedup vs baseline: 1.0064x; 1.0008x over previous
.LBB0_155:
	s_or_b64 exec, exec, s[16:17]
	v_cvt_f32_u32_e32 v3, v0
	s_waitcnt vmcnt(0)
	v_readfirstlane_b32 s3, v2
	s_add_u32 s16, s10, 0x63500
	s_addc_u32 s17, s11, 0
	v_rcp_iflag_f32_e32 v3, v3
	v_add_u32_e32 v1, s3, v1
	v_add_u32_e32 v4, 1, v1
	s_mov_b64 s[18:19], 0
	v_mul_f32_e32 v2, 0x4f7ffffe, v3
	v_cvt_u32_f32_e32 v2, v2
	v_sub_u32_e32 v3, 0, v0
	v_mul_lo_u32 v3, v3, v2
	v_mul_hi_u32 v3, v2, v3
	v_add_u32_e32 v2, v2, v3
	v_mul_hi_u32 v2, v1, v2
	v_mul_lo_u32 v3, v2, v0
	v_sub_u32_e32 v1, v1, v3
	v_add_u32_e32 v5, 1, v2
	v_cmp_ge_u32_e32 vcc, v1, v0
	v_sub_u32_e32 v3, v1, v0
	s_nop 0
	v_cndmask_b32_e32 v2, v2, v5, vcc
	v_cndmask_b32_e32 v1, v1, v3, vcc
	v_add_u32_e32 v3, 1, v2
	v_cmp_ge_u32_e32 vcc, v1, v0
	s_nop 1
	v_cndmask_b32_e32 v2, v2, v3, vcc
	v_mul_lo_u32 v1, v0, v2
	v_add_u32_e32 v0, v1, v0
	v_cmp_ne_u32_e32 vcc, v4, v0
	v_mov_b32_e32 v5, v0
	v_mov_b64_e32 v[0:1], s[16:17]
	s_and_saveexec_b64 s[14:15], vcc
	s_cbranch_execz .LBB0_167
	v_mov_b32_e32 v0, 0
	global_load_dword v1, v0, s[16:17] offset:-256 sc1
	s_mov_b64 s[22:23], 0
	s_waitcnt vmcnt(0)
	v_cmp_lt_u32_e32 vcc, v1, v5
	s_and_saveexec_b64 s[20:21], vcc
	s_cbranch_execz .LBB0_166
	s_add_u32 s18, s10, 0x60200
	s_addc_u32 s19, s11, 0
	s_mov_b32 s3, 1
	s_mov_b64 s[10:11], 0
	s_branch .LBB0_159

.LBB0_163:
	global_load_dword v1, v0, s[16:17] offset:-256 sc1
	s_add_i32 s3, s3, 1
	s_mov_b64 s[24:25], -1
	s_waitcnt vmcnt(0)
	v_cmp_ge_u32_e32 vcc, v1, v5
	s_orn2_b64 s[28:29], vcc, exec
	s_branch .LBB0_158

.LBB0_447:
	s_or_b64 exec, exec, s[14:15]
	v_cvt_f32_u32_e32 v3, v0
	s_waitcnt vmcnt(0)
	v_readfirstlane_b32 s3, v2
	s_add_u32 s14, s4, 0x63500
	s_addc_u32 s15, s5, 0
	v_rcp_iflag_f32_e32 v3, v3
	v_add_u32_e32 v1, s3, v1
	v_add_u32_e32 v4, 1, v1
	s_mov_b64 s[16:17], 0
	v_mul_f32_e32 v2, 0x4f7ffffe, v3
	v_cvt_u32_f32_e32 v2, v2
	v_sub_u32_e32 v3, 0, v0
	v_mul_lo_u32 v3, v3, v2
	v_mul_hi_u32 v3, v2, v3
	v_add_u32_e32 v2, v2, v3
	v_mul_hi_u32 v2, v1, v2
	v_mul_lo_u32 v3, v2, v0
	v_sub_u32_e32 v1, v1, v3
	v_add_u32_e32 v5, 1, v2
	v_cmp_ge_u32_e32 vcc, v1, v0
	v_sub_u32_e32 v3, v1, v0
	s_nop 0
	v_cndmask_b32_e32 v2, v2, v5, vcc
	v_cndmask_b32_e32 v1, v1, v3, vcc
	v_add_u32_e32 v3, 1, v2
	v_cmp_ge_u32_e32 vcc, v1, v0
	s_nop 1
	v_cndmask_b32_e32 v2, v2, v3, vcc
	v_mul_lo_u32 v1, v0, v2
	v_add_u32_e32 v0, v1, v0
	v_cmp_ne_u32_e32 vcc, v4, v0
	v_mov_b32_e32 v5, v0
	v_mov_b64_e32 v[0:1], s[14:15]
	s_and_saveexec_b64 s[12:13], vcc
	s_cbranch_execz .LBB0_459
	v_mov_b32_e32 v0, 0
	global_load_dword v1, v0, s[14:15] offset:-256 sc1
	s_mov_b64 s[20:21], 0
	s_waitcnt vmcnt(0)
	v_cmp_lt_u32_e32 vcc, v1, v5
	s_and_saveexec_b64 s[18:19], vcc
	s_cbranch_execz .LBB0_458
	s_add_u32 s16, s4, 0x60200
	s_addc_u32 s17, s5, 0
	s_mov_b32 s3, 1
	s_mov_b64 s[4:5], 0
	s_branch .LBB0_451

.LBB0_455:
	global_load_dword v1, v0, s[14:15] offset:-256 sc1
	s_add_i32 s3, s3, 1
	s_mov_b64 s[22:23], -1
	s_waitcnt vmcnt(0)
	v_cmp_ge_u32_e32 vcc, v1, v5
	s_orn2_b64 s[26:27], vcc, exec
	s_branch .LBB0_450
